# P3: RS table fill off the critical path (first tile: math under the prologue loads; second tile: inputs loaded at the start of the first tile's epilogue, counted wait instead of vmcnt(0))
# speedup vs baseline: 1.0024x; 1.0024x over previous
; #define PG8_LAS __attribute__((address_space(3)))
; #define PG8_STAGE(bufoff, gbase, voff) do { _Pragma("unroll") for (int _i = 0; _i < 2; ++_i) \
;         __builtin_amdgcn_global_load_lds((const unsigned*)((const char*)(gbase) + (voff)[_i]), (PG8_LAS unsigned*)(lds + (bufoff) + ldsw + _i * 8192), 16, 0, 0); } while (0)
; #define PG8_WAIT_V(n) asm volatile("s_waitcnt vmcnt(" #n ")" ::: "memory")
; #define PG8_BAR __builtin_amdgcn_s_barrier()
; __device__ __forceinline__ void rs_fill(PG8_LAS float* tp, const float* ss, int pm, int tid) {
;     if (tid < 256) { const f32x4* p = (const f32x4*)(ss + (size_t)(pm * 256 + tid) * 16); const f32x4 a = p[0], b1 = p[1], b2 = p[2], c = p[3];
;         const float sa = (a[0] + a[1]) + (a[2] + a[3]), sb = ((b1[0] + b1[1]) + (b1[2] + b1[3])) + ((b2[0] + b2[1]) + (b2[2] + b2[3])), sc = (c[0] + c[1]) + (c[2] + c[3]);
;         const float ra = 1.0f / sqrtf(sa * (1.0f / 1024.0f) + 1e-6f), rb = 1.0f / sqrtf(sb * (1.0f / 1024.0f) + 1e-6f), rc = 1.0f / sqrtf(sc * (1.0f / 1024.0f) + 1e-6f);
;         tp[tid] = ra / rb; tp[256 + tid] = rb / rc; tp[512 + tid] = rc; }
; template <class Epi, class Sched, bool ALIGN_EPI = false, bool SP2 = false, bool RS = false, bool BPRE = false>
; __device__ __forceinline__ void gemm_phase(PG8_LAS unsigned char* lds, const Gemm g, const Sched& S, const Epi& E, const float* rs_ss = nullptr, PG8_LAS float* rs_tab = nullptr) {
;     ...
;     if constexpr (RS) rs_fill(rs_tab, rs_ss, cur.pm, tid);
;     if constexpr (SP2) {
;         PG8_STAGE(PG8_SB(0, 0), cB, voffB); PG8_STAGE(PG8_SB(0, 1), cB + hstep, voffB); PG8_STAGE(PG8_SA(0, 0), cA, voffA); PG8_STAGE(PG8_SA(0, 1), cA + hstep, voffA);
;         if (wr == 1) PG8_BAR;
;         PG8_WAIT_V(2); PG8_BAR;
.LBB0_734:
	s_movk_i32 s0, 0x100
	v_cmp_gt_u32_e64 s[0:1], s0, v0
	s_and_saveexec_b64 s[10:11], s[0:1]
	s_cbranch_execz .LBB0_736
	v_lshl_or_b32 v226, s70, 8, v0
	v_ashrrev_i32_e32 v227, 31, v226
	v_lshlrev_b64 v[226:227], 6, v[226:227]
	v_lshl_add_u64 v[242:243], s[46:47], 0, v[226:227]
	s_waitcnt lgkmcnt(0)
	global_load_dwordx4 v[226:229], v[242:243], off
	global_load_dwordx4 v[230:233], v[242:243], off offset:16
	global_load_dwordx4 v[234:237], v[242:243], off offset:32
	global_load_dwordx4 v[238:241], v[242:243], off offset:48
.LBB0_736:
	s_or_b64 exec, exec, s[10:11]
	s_mul_i32 s5, s70, 0x180000
	s_mul_hi_i32 s4, s70, 0x180000
	s_add_u32 s10, s44, s5
	s_addc_u32 s11, s45, s4
	s_mul_i32 s5, s14, 0x180000
	s_mul_hi_i32 s4, s14, 0x180000
	s_add_u32 s38, s34, s5
	s_addc_u32 s39, s35, s4
	s_lshr_b32 s5, s18, 6
	s_lshl_b32 s54, s5, 10
	s_add_i32 s55, s54, 0
	v_lshlrev_b32_e32 v134, 4, v0
	s_movk_i32 s4, 0x3800
	v_mov_b32_e32 v1, 0x2000
	s_add_i32 m0, s55, 0x10000
	v_bitop3_b32 v3, v134, s4, v1 bitop3:0xc8
	s_waitcnt lgkmcnt(0)
	v_and_b32_e32 v4, 0x7f0, v134
	s_lshr_b32 s4, s18, 8
	global_load_lds_dwordx4 v134, s[38:39]
	s_add_i32 m0, s55, 0x12000
	v_or_b32_e32 v136, v3, v4
	s_add_u32 s6, s38, 0xc0000
	global_load_lds_dwordx4 v136, s[38:39]
	s_addc_u32 s7, s39, 0
	s_add_i32 m0, s55, 0x14000
	s_add_i32 s56, s55, 0x2000
	global_load_lds_dwordx4 v134, s[6:7]
	s_add_i32 m0, s55, 0x16000
	v_mov_b32_e32 v2, 0
	global_load_lds_dwordx4 v136, s[6:7]
	s_mov_b32 m0, s55
	s_add_u32 s6, s10, 0xc0000
	global_load_lds_dwordx4 v134, s[10:11]
	s_mov_b32 m0, s56
	s_addc_u32 s7, s11, 0
	s_add_i32 s57, s55, 0x4000
	global_load_lds_dwordx4 v136, s[10:11]
	s_mov_b32 m0, s57
	s_add_i32 s58, s55, 0x6000
	global_load_lds_dwordx4 v134, s[6:7]
	s_mov_b32 m0, s58
	s_cmp_eq_u32 s4, 1
	global_load_lds_dwordx4 v136, s[6:7]
	s_and_saveexec_b64 s[92:93], s[0:1]
	s_cbranch_execz .Lrsf_a
	s_waitcnt vmcnt(8)
	v_mov_b32_e32 v225, 0x358637bd
	s_mov_b32 s88, 0xf800000
	v_mov_b32_e32 v242, 0x260
	v_add_f32_e32 v226, v226, v227
	v_add_f32_e32 v227, v228, v229
	v_add_f32_e32 v228, v230, v231
	v_add_f32_e32 v229, v232, v233
	v_add_f32_e32 v230, v234, v235
	v_add_f32_e32 v231, v236, v237
	v_add_f32_e32 v226, v226, v227
	v_add_f32_e32 v227, v228, v229
	v_add_f32_e32 v228, v230, v231
	v_fmamk_f32 v226, v226, 0x3a800000, v225
	v_add_f32_e32 v232, v238, v239
	v_add_f32_e32 v233, v240, v241
	v_add_f32_e32 v227, v227, v228
	v_mul_f32_e32 v228, 0x4f800000, v226
	v_cmp_gt_f32_e32 vcc, s88, v226
	v_add_f32_e32 v229, v232, v233
	v_fmamk_f32 v227, v227, 0x3a800000, v225
	v_cndmask_b32_e32 v226, v226, v228, vcc
	v_fmac_f32_e32 v225, 0x3a800000, v229
	v_mul_f32_e32 v228, 0x4f800000, v227
	v_sqrt_f32_e32 v230, v226
	v_cmp_gt_f32_e64 s[86:87], s88, v227
	v_mul_f32_e32 v229, 0x4f800000, v225
	v_cmp_gt_f32_e64 s[88:89], s88, v225
	v_cndmask_b32_e64 v227, v227, v228, s[86:87]
	v_sqrt_f32_e32 v228, v227
	v_cndmask_b32_e64 v225, v225, v229, s[88:89]
	v_sqrt_f32_e32 v229, v225
	v_add_u32_e32 v231, -1, v230
	v_add_u32_e32 v232, 1, v230
	v_fma_f32 v233, -v231, v230, v226
	v_fma_f32 v234, -v232, v230, v226
	v_add_u32_e32 v235, -1, v228
	v_cmp_ge_f32_e64 s[90:91], 0, v233
	v_add_u32_e32 v237, -1, v229
	v_add_u32_e32 v236, 1, v228
	v_cndmask_b32_e64 v230, v230, v231, s[90:91]
	v_fma_f32 v231, -v235, v228, v227
	v_cmp_lt_f32_e64 s[90:91], 0, v234
	v_fma_f32 v239, -v237, v229, v225
	v_add_u32_e32 v238, 1, v229
	v_cndmask_b32_e64 v230, v230, v232, s[90:91]
	v_cmp_ge_f32_e64 s[90:91], 0, v231
	v_fma_f32 v233, -v236, v228, v227
	v_fma_f32 v240, -v238, v229, v225
	v_cndmask_b32_e64 v228, v228, v235, s[90:91]
	v_cmp_ge_f32_e64 s[90:91], 0, v239
	v_mul_f32_e32 v231, 0x37800000, v230
	v_cndmask_b32_e32 v230, v230, v231, vcc
	v_cndmask_b32_e64 v229, v229, v237, s[90:91]
	v_cmp_lt_f32_e64 s[90:91], 0, v233
	v_cmp_class_f32_e32 vcc, v226, v242
	s_nop 0
	v_cndmask_b32_e64 v228, v228, v236, s[90:91]
	v_cmp_lt_f32_e64 s[90:91], 0, v240
	v_mul_f32_e32 v231, 0x37800000, v228
	v_cndmask_b32_e32 v226, v230, v226, vcc
	v_cndmask_b32_e64 v229, v229, v238, s[90:91]
	v_cndmask_b32_e64 v228, v228, v231, s[86:87]
	v_div_scale_f32 v230, s[86:87], v226, v226, 1.0
	v_mul_f32_e32 v232, 0x37800000, v229
	v_cmp_class_f32_e64 s[86:87], v227, v242
	v_cndmask_b32_e64 v229, v229, v232, s[88:89]
	v_div_scale_f32 v231, vcc, 1.0, v226, 1.0
	v_cndmask_b32_e64 v227, v228, v227, s[86:87]
	v_cmp_class_f32_e64 s[86:87], v225, v242
	v_rcp_f32_e32 v228, v230
	s_nop 0
	v_cndmask_b32_e64 v225, v229, v225, s[86:87]
	v_div_scale_f32 v229, s[86:87], v227, v227, 1.0
	v_div_scale_f32 v233, s[88:89], v225, v225, 1.0
	v_rcp_f32_e32 v235, v229
	v_rcp_f32_e32 v236, v233
	v_fma_f32 v237, -v230, v228, 1.0
	v_fmac_f32_e32 v228, v237, v228
	v_fma_f32 v237, -v229, v235, 1.0
	v_div_scale_f32 v232, s[86:87], 1.0, v227, 1.0
	v_fma_f32 v238, -v233, v236, 1.0
	v_mul_f32_e32 v239, v231, v228
	v_fmac_f32_e32 v235, v237, v235
	v_fmac_f32_e32 v236, v238, v236
	v_fma_f32 v237, -v230, v239, v231
	v_mul_f32_e32 v238, v232, v235
	v_fmac_f32_e32 v239, v237, v228
	v_fma_f32 v237, -v229, v238, v232
	v_fma_f32 v230, -v230, v239, v231
	v_fmac_f32_e32 v238, v237, v235
	v_div_fmas_f32 v228, v230, v228, v239
	v_fma_f32 v229, -v229, v238, v232
	s_mov_b64 vcc, s[86:87]
	v_div_fixup_f32 v226, v228, v226, 1.0
	v_div_fmas_f32 v228, v229, v235, v238
	v_div_scale_f32 v234, s[88:89], 1.0, v225, 1.0
	v_div_fixup_f32 v227, v228, v227, 1.0
	v_mul_f32_e32 v240, v234, v236
	v_div_scale_f32 v228, s[86:87], v227, v227, v226
	v_fma_f32 v241, -v233, v240, v234
	v_rcp_f32_e32 v229, v228
	v_fmac_f32_e32 v240, v241, v236
	v_fma_f32 v230, -v233, v240, v234
	s_mov_b64 vcc, s[88:89]
	v_div_fmas_f32 v230, v230, v236, v240
	v_div_fixup_f32 v225, v230, v225, 1.0
	v_fma_f32 v230, -v228, v229, 1.0
	v_fmac_f32_e32 v229, v230, v229
	v_div_scale_f32 v230, vcc, v226, v227, v226
	v_mul_f32_e32 v231, v230, v229
	v_fma_f32 v232, -v228, v231, v230
	v_fmac_f32_e32 v231, v232, v229
	v_fma_f32 v228, -v228, v231, v230
	v_div_fmas_f32 v228, v228, v229, v231
	v_div_scale_f32 v229, s[86:87], v225, v225, v227
	v_rcp_f32_e32 v230, v229
	v_div_fixup_f32 v226, v228, v227, v226
	v_lshl_add_u32 v228, v0, 2, 0
	v_add_u32_e32 v228, 0x20000, v228
	v_fma_f32 v231, -v229, v230, 1.0
	v_fmac_f32_e32 v230, v231, v230
	v_div_scale_f32 v231, vcc, v227, v225, v227
	v_mul_f32_e32 v232, v231, v230
	v_fma_f32 v233, -v229, v232, v231
	v_fmac_f32_e32 v232, v233, v230
	v_fma_f32 v229, -v229, v232, v231
	v_div_fmas_f32 v229, v229, v230, v232
	v_div_fixup_f32 v227, v229, v225, v227
	ds_write2st64_b32 v228, v226, v227 offset1:4
	ds_write_b32 v228, v225 offset:2048
.Lrsf_a:
	s_or_b64 exec, exec, s[92:93]
	s_cmp_eq_u32 s4, 1
	s_mov_b32 s15, 0
	v_mov_b32_e32 v135, v2
	s_cselect_b64 s[16:17], -1, 0
	s_cmp_lg_u32 s4, 1
	v_mov_b32_e32 v137, v2
	s_cbranch_scc1 .LBB0_738
	s_barrier

; __device__ __forceinline__ void rs_fill(PG8_LAS float* tp, const float* ss, int pm, int tid) {
;     if (tid < 256) { const f32x4* p = (const f32x4*)(ss + (size_t)(pm * 256 + tid) * 16); const f32x4 a = p[0], b1 = p[1], b2 = p[2], c = p[3];
;     __device__ __forceinline__ void operator()(const f32x4 (&acc)[2][2][4][2], const pg8::Unit& u, int wr, int wc, int fr, int fq, const LAS float* tab) const {
;     ...
;                 const int row = row0 + ai * 128 + m * 16;
;                 bf16_t* rowp = (mode == 0) ? base + (size_t)(row >> 4) * 4096 + (size_t)(wc * 512 + (row & 15) * 32 + 8 * fq) : base + (size_t)row * ldc + col0;
;                 const int bjstep = (mode == 0) ? 4 * 512 : 128;
;                 float s1 = 0.f, s2 = 0.f;
;                 const float f2 = (kind == 4) ? tab[512 + ai * 128 + wr * 64 + m * 16 + fr] : 1.0f;
; #pragma unroll
;                 for (int bj = 0; bj < 2; ++bj) {
;                     f32x4 v0 = acc[ai][bj][m][0], v1 = acc[ai][bj][m][1];
;                     if (kind == 1) {
; #pragma unroll
;                         for (int e = 0; e < 4; ++e) { v0[e] = silu_f(v0[e]); v1[e] = silu_f(v1[e]); }
;                     } else if (kind == 2) { v0 = v0 * QSCALE; v1 = v1 * QSCALE; }
;                     else if (kind == 3) {
; #pragma unroll
;                         for (int e = 0; e < 4; ++e) { s1 += v0[e] + v1[e]; s2 += v0[e] * v0[e] + v1[e] * v1[e]; }
;                     } else if (kind == 4) {
;                         v0 = v0 * f2; v1 = v1 * f2;
; #pragma unroll
;                         for (int e = 0; e < 4; ++e) s2 += v0[e] * v0[e] + v1[e] * v1[e];
;                     }
;                     u32x4 w; w.x = cvt_pk_bf16(v0[0], v0[1]); w.y = cvt_pk_bf16(v0[2], v0[3]); w.z = cvt_pk_bf16(v1[0], v1[1]); w.w = cvt_pk_bf16(v1[2], v1[3]);
;                     *(u32x4*)(rowp + bj * bjstep) = w;
;                 }
;                 if (kind == 3) {
;                     s1 += __shfl_xor(s1, 16); s1 += __shfl_xor(s1, 32); s2 += __shfl_xor(s2, 16); s2 += __shfl_xor(s2, 32);
;                     if (fq == 0) { float* p = aux + (size_t)row * 32 + ((pn - 12) * 4 + wc) * 2; p[0] = s1; p[1] = s2; }
;                 } else if (kind == 4) {
;                     s2 += __shfl_xor(s2, 16); s2 += __shfl_xor(s2, 32);
;                     if (fq == 0) aux[(size_t)row * 32 + pn * 4 + wc] = s2;
.LBB0_761:
	v_lshl_or_b32 v240, s69, 8, v0
	v_ashrrev_i32_e32 v241, 31, v240
	v_lshlrev_b64 v[240:241], 6, v[240:241]
	v_lshl_add_u64 v[240:241], s[46:47], 0, v[240:241]
	global_load_dwordx4 v[224:227], v[240:241], off
	global_load_dwordx4 v[228:231], v[240:241], off offset:16
	global_load_dwordx4 v[232:235], v[240:241], off offset:32
	global_load_dwordx4 v[236:239], v[240:241], off offset:48
	ds_read_b32 v148, v158 offset:2048
	v_lshl_or_b32 v146, s14, 8, v153
	v_lshl_add_u32 v4, s70, 8, v1
	v_ashrrev_i32_e32 v147, 31, v146
	v_ashrrev_i32_e32 v5, 31, v4
	s_waitcnt lgkmcnt(0)
	v_pk_mul_f32 v[162:163], v[128:129], v[148:149] op_sel_hi:[1,0]
	v_pk_mul_f32 v[128:129], v[126:127], v[148:149] op_sel_hi:[1,0]
	v_pk_mul_f32 v[130:131], v[130:131], v[148:149] op_sel_hi:[1,0]
	v_mul_f32_e32 v3, v128, v128
	v_mul_f32_e32 v126, v129, v129
	v_fmac_f32_e32 v3, v130, v130
	v_fmac_f32_e32 v126, v131, v131
	v_pk_mul_f32 v[132:133], v[132:133], v[148:149] op_sel_hi:[1,0]
	v_add_f32_e32 v3, v3, v126
	v_mul_f32_e32 v126, v162, v162
	v_fmac_f32_e32 v126, v132, v132
	v_add_f32_e32 v3, v126, v3
	v_mul_f32_e32 v126, v163, v163
	v_fmac_f32_e32 v126, v133, v133
	v_add_f32_e32 v3, v126, v3
	v_cvt_pk_bf16_f32 v126, v130, v131
	v_cvt_pk_bf16_f32 v127, v132, v133
	v_pk_mul_f32 v[132:133], v[118:119], v[148:149] op_sel_hi:[1,0]
	v_pk_mul_f32 v[122:123], v[122:123], v[148:149] op_sel_hi:[1,0]
	v_mul_f32_e32 v118, v132, v132
	v_fmac_f32_e32 v118, v122, v122
	v_add_f32_e32 v3, v118, v3
	v_mul_f32_e32 v118, v133, v133
	v_pk_mul_f32 v[130:131], v[120:121], v[148:149] op_sel_hi:[1,0]
	v_fmac_f32_e32 v118, v123, v123
	v_pk_mul_f32 v[124:125], v[124:125], v[148:149] op_sel_hi:[1,0]
	v_add_f32_e32 v3, v118, v3
	v_mul_f32_e32 v118, v130, v130
	v_fmac_f32_e32 v118, v124, v124
	v_add_f32_e32 v3, v118, v3
	v_mul_f32_e32 v118, v131, v131
	v_fmac_f32_e32 v118, v125, v125
	v_and_b32_e32 v119, 64, v157
	v_add_f32_e32 v118, v118, v3
	v_xor_b32_e32 v3, 16, v157
	v_add_u32_e32 v119, 64, v119
	v_cmp_lt_i32_e32 vcc, v3, v119
	v_lshl_add_u64 v[146:147], v[146:147], 1, s[30:31]
	s_lshl_b32 s6, s14, 2
	v_cndmask_b32_e32 v3, v157, v3, vcc
	v_lshlrev_b32_e32 v3, 2, v3
	ds_bpermute_b32 v120, v3, v118
	v_lshlrev_b64 v[160:161], 12, v[4:5]
	s_ashr_i32 s7, s6, 31
	v_lshl_add_u64 v[160:161], v[146:147], 0, v[160:161]
	v_cvt_pk_bf16_f32 v128, v128, v129
	s_waitcnt lgkmcnt(0)
	v_add_f32_e32 v118, v118, v120
	v_xor_b32_e32 v120, 32, v157
	v_cmp_lt_i32_e32 vcc, v120, v119
	v_cvt_pk_bf16_f32 v129, v162, v163
	global_store_dwordx4 v[160:161], v[126:129], off
	v_cvt_pk_bf16_f32 v122, v122, v123
	v_cvt_pk_bf16_f32 v123, v124, v125
	v_cvt_pk_bf16_f32 v124, v132, v133
	s_nop 0
	v_cndmask_b32_e32 v119, v157, v120, vcc
	v_lshlrev_b32_e32 v120, 2, v119
	ds_bpermute_b32 v119, v120, v118
	v_cvt_pk_bf16_f32 v125, v130, v131
	global_store_dwordx4 v[160:161], v[122:125], off offset:256
	s_and_saveexec_b64 s[10:11], s[8:9]
	s_cbranch_execz .LBB0_763
	v_lshlrev_b64 v[122:123], 7, v[4:5]
	v_lshl_add_u64 v[122:123], s[12:13], 0, v[122:123]
	v_lshl_add_u64 v[122:123], s[6:7], 2, v[122:123]
	s_lshl_b32 s14, s59, 2
	v_lshl_add_u64 v[122:123], v[122:123], 0, s[14:15]
	s_waitcnt lgkmcnt(0)
	v_add_f32_e32 v5, v118, v119
	global_store_dword v[122:123], v5, off

; #define PG8_LAS __attribute__((address_space(3)))
; __device__ __forceinline__ void rs_fill(PG8_LAS float* tp, const float* ss, int pm, int tid) {
;     if (tid < 256) { const f32x4* p = (const f32x4*)(ss + (size_t)(pm * 256 + tid) * 16); const f32x4 a = p[0], b1 = p[1], b2 = p[2], c = p[3];
;         const float sa = (a[0] + a[1]) + (a[2] + a[3]), sb = ((b1[0] + b1[1]) + (b1[2] + b1[3])) + ((b2[0] + b2[1]) + (b2[2] + b2[3])), sc = (c[0] + c[1]) + (c[2] + c[3]);
;         const float ra = 1.0f / sqrtf(sa * (1.0f / 1024.0f) + 1e-6f), rb = 1.0f / sqrtf(sb * (1.0f / 1024.0f) + 1e-6f), rc = 1.0f / sqrtf(sc * (1.0f / 1024.0f) + 1e-6f);
;         tp[tid] = ra / rb; tp[256 + tid] = rb / rc; tp[512 + tid] = rc; }
; template <class Epi, class Sched, bool ALIGN_EPI = false, bool SP2 = false, bool RS = false, bool BPRE = false>
; __device__ __forceinline__ void gemm_phase(PG8_LAS unsigned char* lds, const Gemm g, const Sched& S, const Epi& E, const float* rs_ss = nullptr, PG8_LAS float* rs_tab = nullptr) {
;     ...
;         if constexpr (RS) rs_fill(rs_tab + (ui & 1) * 768, rs_ss, cur.pm, tid);
.LBB0_777:
	s_or_b64 exec, exec, s[10:11]
	s_and_b64 vcc, exec, s[4:5]
	s_mov_b64 s[4:5], -1
	s_cbranch_vccnz .LBB0_740
	s_and_saveexec_b64 s[38:39], s[0:1]
	s_cbranch_execz .LBB0_780
	s_waitcnt lgkmcnt(0)
	s_bitcmp1_b32 s67, 0
	s_cselect_b32 s14, 0xc00, 0
	s_waitcnt vmcnt(16)
	v_add_f32_e32 v3, v224, v225
	v_add_f32_e32 v4, v226, v227
	v_add_f32_e32 v5, v228, v229
	v_add_f32_e32 v6, v230, v231
	v_add_f32_e32 v7, v232, v233
	v_add_f32_e32 v8, v234, v235
	v_add_f32_e32 v9, v236, v237
	v_add_f32_e32 v10, v238, v239
	v_add_f32_e32 v3, v3, v4
	v_add_f32_e32 v4, v5, v6
	v_add_f32_e32 v5, v7, v8
	v_add_f32_e32 v6, v9, v10
	v_fmamk_f32 v3, v3, 0x3a800000, v155
	v_add_f32_e32 v4, v4, v5
	v_fmamk_f32 v5, v6, 0x3a800000, v155
	v_mul_f32_e32 v6, 0x4f800000, v3
	v_cmp_gt_f32_e32 vcc, s66, v3
	v_fmamk_f32 v4, v4, 0x3a800000, v155
	v_mul_f32_e32 v7, 0x4f800000, v5
	v_cndmask_b32_e32 v3, v3, v6, vcc
	v_cmp_gt_f32_e64 s[4:5], s66, v5
	v_mul_f32_e32 v6, 0x4f800000, v4
	v_cmp_gt_f32_e64 s[6:7], s66, v4
	v_cndmask_b32_e64 v5, v5, v7, s[4:5]
	v_sqrt_f32_e32 v7, v3
	v_cndmask_b32_e64 v4, v4, v6, s[6:7]
	v_sqrt_f32_e32 v6, v5
	v_sqrt_f32_e32 v8, v4
	v_add_u32_e32 v9, -1, v7
	v_fma_f32 v13, -v9, v7, v3
	v_add_u32_e32 v11, -1, v6
	v_add_u32_e32 v10, 1, v7
	v_fma_f32 v17, -v11, v6, v5
	v_cmp_ge_f32_e64 s[10:11], 0, v13
	v_add_u32_e32 v12, 1, v6
	v_fma_f32 v14, -v10, v7, v3
	v_add_u32_e32 v15, -1, v8
	v_cndmask_b32_e64 v7, v7, v9, s[10:11]
	v_cmp_ge_f32_e64 s[10:11], 0, v17
	v_fma_f32 v18, -v12, v6, v5
	v_fma_f32 v9, -v15, v8, v4
	v_cndmask_b32_e64 v6, v6, v11, s[10:11]
	v_cmp_lt_f32_e64 s[10:11], 0, v14
	v_add_u32_e32 v16, 1, v8
	v_fma_f32 v13, -v16, v8, v4
	v_cndmask_b32_e64 v7, v7, v10, s[10:11]
	v_cmp_ge_f32_e64 s[10:11], 0, v9
	v_mul_f32_e32 v9, 0x37800000, v7
	v_cndmask_b32_e32 v7, v7, v9, vcc
	v_cndmask_b32_e64 v8, v8, v15, s[10:11]
	v_cmp_lt_f32_e64 s[10:11], 0, v18
	v_cmp_class_f32_e32 vcc, v3, v156
	s_nop 0
	v_cndmask_b32_e64 v6, v6, v12, s[10:11]
	v_cmp_lt_f32_e64 s[10:11], 0, v13
	v_mul_f32_e32 v10, 0x37800000, v6
	v_cndmask_b32_e64 v6, v6, v10, s[4:5]
	v_cndmask_b32_e64 v8, v8, v16, s[10:11]
	v_cndmask_b32_e32 v3, v7, v3, vcc
	v_cmp_class_f32_e32 vcc, v5, v156
	v_mul_f32_e32 v9, 0x37800000, v8
	v_cndmask_b32_e64 v7, v8, v9, s[6:7]
	v_cndmask_b32_e32 v5, v6, v5, vcc
	v_div_scale_f32 v6, s[4:5], v3, v3, 1.0
	v_cmp_class_f32_e64 s[4:5], v4, v156
	v_rcp_f32_e32 v10, v6
	v_div_scale_f32 v8, vcc, 1.0, v3, 1.0
	v_cndmask_b32_e64 v4, v7, v4, s[4:5]
	v_div_scale_f32 v7, s[4:5], v5, v5, 1.0
	v_div_scale_f32 v11, s[6:7], v4, v4, 1.0
	v_rcp_f32_e32 v12, v7
	v_rcp_f32_e32 v14, v11
	v_fma_f32 v15, -v6, v10, 1.0
	v_fmac_f32_e32 v10, v15, v10
	v_fma_f32 v16, -v7, v12, 1.0
	v_fma_f32 v15, -v11, v14, 1.0
	v_div_scale_f32 v13, s[6:7], 1.0, v4, 1.0
	v_fmac_f32_e32 v12, v16, v12
	v_mul_f32_e32 v16, v8, v10
	v_fmac_f32_e32 v14, v15, v14
	v_fma_f32 v17, -v6, v16, v8
	v_mul_f32_e32 v18, v13, v14
	v_fmac_f32_e32 v16, v17, v10
	v_fma_f32 v17, -v11, v18, v13
	v_fma_f32 v6, -v6, v16, v8
	v_fmac_f32_e32 v18, v17, v14
	v_div_fmas_f32 v6, v6, v10, v16
	v_fma_f32 v8, -v11, v18, v13
	s_mov_b64 vcc, s[6:7]
	v_div_fixup_f32 v3, v6, v3, 1.0
	v_div_fmas_f32 v6, v8, v14, v18
	v_div_scale_f32 v9, s[4:5], 1.0, v5, 1.0
	v_div_fixup_f32 v4, v6, v4, 1.0
	v_mul_f32_e32 v15, v9, v12
	v_div_scale_f32 v6, s[6:7], v4, v4, v3
	v_fma_f32 v19, -v7, v15, v9
	v_rcp_f32_e32 v8, v6
	v_fmac_f32_e32 v15, v19, v12
	v_fma_f32 v7, -v7, v15, v9
	s_mov_b64 vcc, s[4:5]
	v_div_fmas_f32 v7, v7, v12, v15
	v_div_fixup_f32 v5, v7, v5, 1.0
	v_fma_f32 v7, -v6, v8, 1.0
	v_fmac_f32_e32 v8, v7, v8
	v_div_scale_f32 v7, vcc, v3, v4, v3
	v_mul_f32_e32 v9, v7, v8
	v_fma_f32 v10, -v6, v9, v7
	v_fmac_f32_e32 v9, v10, v8
	v_fma_f32 v6, -v6, v9, v7
	v_div_scale_f32 v7, s[4:5], v5, v5, v4
	v_rcp_f32_e32 v10, v7
	v_div_fmas_f32 v6, v6, v8, v9
	v_div_fixup_f32 v3, v6, v4, v3
	v_add_u32_e32 v6, s14, v152
	v_fma_f32 v8, -v7, v10, 1.0
	v_fmac_f32_e32 v10, v8, v10
	v_div_scale_f32 v8, vcc, v4, v5, v4
	v_mul_f32_e32 v9, v8, v10
	v_fma_f32 v11, -v7, v9, v8
	v_fmac_f32_e32 v9, v11, v10
	v_fma_f32 v7, -v7, v9, v8
	v_div_fmas_f32 v7, v7, v10, v9
	v_div_fixup_f32 v4, v7, v5, v4
	ds_write2st64_b32 v6, v3, v4 offset1:4
	ds_write_b32 v6, v5 offset:2048
